# MLP-up: the 32 last-round tiles cut into two half tiles (A rows 0-127 / 128-255) on 64 workgroups; other half's MFMA blocks and stores branched over
# baseline (speedup 1.0000x reference)
.LBB0_59:
	s_or_b64 exec, exec, s[4:5]
	s_add_u32 s4, s76, 0x800
	s_addc_u32 s5, s77, 0
	v_writelane_b32 v252, s4, 39
	s_add_u32 s3, s76, 0x10120000
	v_lshrrev_b32_e32 v165, 4, v164
	v_writelane_b32 v252, s5, 40
	v_writelane_b32 v252, s3, 41
	s_addc_u32 s3, s77, 0
	v_writelane_b32 v252, s3, 42
	s_add_u32 s3, s76, 0x10340000
	v_writelane_b32 v252, s3, 43
	s_addc_u32 s3, s77, 0
	s_add_u32 s4, s76, 0x1300000
	v_writelane_b32 v252, s3, 44
	s_addc_u32 s5, s77, 0
	v_writelane_b32 v252, s4, 45
	v_mbcnt_lo_u32_b32 v209, -1, 0
	v_lshl_add_u32 v204, v164, 4, 0
	v_writelane_b32 v252, s5, 46
	s_add_u32 s4, s76, 0x1b00000
	s_addc_u32 s5, s77, 0
	v_writelane_b32 v252, s4, 47
	v_mov_b32_e32 v205, 0x358637bd
	v_mov_b32_e32 v211, 1
	v_writelane_b32 v252, s5, 48
	s_add_u32 s4, s76, 0x3b00000
	s_addc_u32 s5, s77, 0
	v_writelane_b32 v252, s4, 49
	v_mov_b32_e32 v208, 0x3c23d70a
	v_mbcnt_hi_u32_b32 v210, -1, v209
	v_writelane_b32 v252, s5, 50
	s_add_u32 s4, s76, 0x5b00000
	s_addc_u32 s5, s77, 0
	v_writelane_b32 v252, s4, 51
	v_mov_b32_e32 v112, 0
	v_mov_b32_e32 v212, 0xf149f2ca
	v_writelane_b32 v252, s5, 52
	s_add_u32 s4, s76, 0x7300000
	s_addc_u32 s5, s77, 0
	v_writelane_b32 v252, s4, 53
	v_mov_b64_e32 v[174:175], 0xff
	v_mov_b64_e32 v[176:177], 0x440
	v_writelane_b32 v252, s5, 54
	s_add_u32 s4, s76, 0x7b00000
	s_addc_u32 s5, s77, 0
	v_writelane_b32 v252, s4, 55
	v_mov_b64_e32 v[178:179], 0x43f
	v_mov_b64_e32 v[180:181], 0x140
	v_writelane_b32 v252, s5, 56
	s_add_u32 s4, s76, 0x9b00000
	s_addc_u32 s5, s77, 0
	s_add_u32 s10, s76, 0x12100000
	s_addc_u32 s11, s77, 0
	s_add_u32 s86, s76, 0x16500000
	v_writelane_b32 v252, s4, 57
	s_addc_u32 s87, s77, 0
	v_mov_b64_e32 v[182:183], 0x13f
	v_writelane_b32 v252, s5, 58
	s_add_u32 s4, s76, 0x18700000
	s_addc_u32 s5, s77, 0
	v_writelane_b32 v252, s4, 59
	s_add_u32 s26, s76, 0x1a900000
	s_addc_u32 s27, s77, 0
	v_writelane_b32 v252, s5, 60
	s_ashr_i32 s31, s82, 31
	v_readlane_b32 s36, v252, 23
	s_ashr_i32 s3, s2, 31
	v_readlane_b32 s44, v252, 31
	v_readlane_b32 s45, v252, 32
	s_add_u32 s4, s44, 0x4000000
	s_addc_u32 s5, s45, 0
	v_readlane_b32 s37, v252, 24
	v_readlane_b32 s38, v252, 25
	v_readlane_b32 s39, v252, 26
	v_readlane_b32 s40, v252, 27
	v_readlane_b32 s41, v252, 28
	v_readlane_b32 s42, v252, 29
	v_readlane_b32 s43, v252, 30
	v_readlane_b32 s46, v252, 33
	v_readlane_b32 s47, v252, 34
	v_readlane_b32 s48, v252, 35
	v_readlane_b32 s49, v252, 36
	v_readlane_b32 s50, v252, 37
	v_readlane_b32 s51, v252, 38
	v_writelane_b32 v252, s4, 61
	s_add_u32 s18, s42, 0x2000
	s_addc_u32 s19, s43, 0
	v_writelane_b32 v252, s5, 62
	s_movk_i32 s91, 0x6000
	v_readlane_b32 s34, v252, 22
	s_lshl_b32 s74, s34, 2
	s_cmp_lg_u64 s[42:43], 0
	s_cselect_b64 s[20:21], -1, 0
	s_add_u32 s84, s76, 0x40200
	s_addc_u32 s85, s77, 0
	s_add_u32 s58, s76, 0x40400
	s_addc_u32 s59, s77, 0
	s_add_u32 s60, s76, 0x40500
	s_addc_u32 s61, s77, 0
	s_add_u32 s62, s76, 0x40600
	s_addc_u32 s63, s77, 0
	s_add_u32 s56, s76, 0x40700
	s_addc_u32 s57, s77, 0
	s_add_u32 s22, s76, 0x40800
	s_addc_u32 s23, s77, 0
	s_add_u32 s4, s76, 0x40900
	s_addc_u32 s5, s77, 0
	v_writelane_b32 v252, s4, 63
	v_writelane_b32 v255, s84, 0
	s_movk_i32 s94, 0x1fff
	v_writelane_b32 v253, s5, 0
	s_add_u32 s4, s76, 0x40a00
	s_addc_u32 s5, s77, 0
	v_writelane_b32 v253, s4, 1
	v_writelane_b32 v255, s85, 1
	v_writelane_b32 v255, s58, 2
	v_writelane_b32 v253, s5, 2
	s_add_u32 s4, s76, 0x40b00
	s_addc_u32 s5, s77, 0
	v_writelane_b32 v253, s4, 3
	v_writelane_b32 v255, s59, 3
	v_writelane_b32 v255, s60, 4
	v_writelane_b32 v253, s5, 4
	s_add_u32 s4, s76, 0x40c00
	s_addc_u32 s5, s77, 0
	v_writelane_b32 v253, s4, 5
	v_writelane_b32 v255, s61, 5
	v_writelane_b32 v255, s62, 6
	v_writelane_b32 v253, s5, 6
	s_add_u32 s4, s76, 0x40d00
	s_addc_u32 s5, s77, 0
	v_writelane_b32 v253, s4, 7
	v_writelane_b32 v255, s63, 7
	v_writelane_b32 v255, s56, 8
	v_writelane_b32 v253, s5, 8
	s_add_u32 s4, s76, 0x40e00
	s_addc_u32 s5, s77, 0
	v_writelane_b32 v253, s4, 9
	v_writelane_b32 v255, s57, 9
	s_nop 0
	v_writelane_b32 v253, s5, 10
	s_add_u32 s4, s76, 0x40f00
	s_addc_u32 s5, s77, 0
	v_writelane_b32 v253, s4, 11
	s_nop 1
	v_writelane_b32 v253, s5, 12
	s_add_u32 s4, s76, 0x41000
	s_addc_u32 s5, s77, 0
	v_writelane_b32 v253, s4, 13
	s_nop 1
	v_writelane_b32 v253, s5, 14
	s_add_u32 s4, s76, 0x41100
	s_addc_u32 s5, s77, 0
	v_writelane_b32 v253, s4, 15
	s_nop 1
	v_writelane_b32 v253, s5, 16
	s_add_u32 s4, s76, 0x41200
	s_addc_u32 s5, s77, 0
	v_writelane_b32 v253, s4, 17
	s_nop 1
	v_writelane_b32 v253, s5, 18
	s_add_u32 s4, s76, 0x41300
	s_addc_u32 s5, s77, 0
	v_writelane_b32 v253, s4, 19
	s_cmp_eq_u32 s8, 15
	s_nop 0
	v_writelane_b32 v253, s5, 20
	s_cselect_b64 s[4:5], -1, 0
	v_writelane_b32 v253, s4, 21
	s_cmp_eq_u32 s8, 14
	s_nop 0
	v_writelane_b32 v253, s5, 22
	s_cselect_b64 s[4:5], -1, 0
	v_writelane_b32 v253, s4, 23
	s_cmp_eq_u32 s8, 13
	s_nop 0
	v_writelane_b32 v253, s5, 24
	s_cselect_b64 s[4:5], -1, 0
	v_writelane_b32 v253, s4, 25
	s_cmp_eq_u32 s8, 12
	s_nop 0
	v_writelane_b32 v253, s5, 26
	s_cselect_b64 s[4:5], -1, 0
	v_writelane_b32 v253, s4, 27
	s_cmp_eq_u32 s8, 11
	s_nop 0
	v_writelane_b32 v253, s5, 28
	s_cselect_b64 s[4:5], -1, 0
	v_writelane_b32 v253, s4, 29
	s_cmp_eq_u32 s8, 10
	s_nop 0
	v_writelane_b32 v253, s5, 30
	s_cselect_b64 s[4:5], -1, 0
	v_writelane_b32 v253, s4, 31
	s_cmp_eq_u32 s8, 9
	s_nop 0
	v_writelane_b32 v253, s5, 32
	s_cselect_b64 s[4:5], -1, 0
	v_writelane_b32 v253, s4, 33
	s_cmp_eq_u32 s8, 8
	s_nop 0
	v_writelane_b32 v253, s5, 34
	s_cselect_b64 s[4:5], -1, 0
	v_writelane_b32 v253, s4, 35
	s_cmp_eq_u32 s8, 7
	s_nop 0
	v_writelane_b32 v253, s5, 36
	s_cselect_b64 s[4:5], -1, 0
	v_writelane_b32 v253, s4, 37
	s_cmp_eq_u32 s8, 6
	s_nop 0
	v_writelane_b32 v253, s5, 38
	s_cselect_b64 s[4:5], -1, 0
	v_writelane_b32 v253, s4, 39
	s_cmp_eq_u32 s8, 5
	s_nop 0
	v_writelane_b32 v253, s5, 40
	s_cselect_b64 s[4:5], -1, 0
	v_writelane_b32 v253, s4, 41
	s_cmp_eq_u32 s8, 4
	s_nop 0
	v_writelane_b32 v253, s5, 42
	s_cselect_b64 s[4:5], -1, 0
	v_writelane_b32 v253, s4, 43
	s_cmp_eq_u32 s8, 3
	s_nop 0
	v_writelane_b32 v253, s5, 44
	s_cselect_b64 s[4:5], -1, 0
	v_writelane_b32 v253, s4, 45
	s_cmp_eq_u32 s8, 2
	s_nop 0
	v_writelane_b32 v253, s5, 46
	s_cselect_b64 s[4:5], -1, 0
	v_writelane_b32 v253, s4, 47
	s_cmp_eq_u32 s8, 1
	s_nop 0
	v_writelane_b32 v253, s5, 48
	s_cselect_b64 s[4:5], -1, 0
	v_writelane_b32 v253, s4, 49
	s_cmp_eq_u32 s8, 0
	s_nop 0
	v_writelane_b32 v253, s5, 50
	s_cselect_b64 s[4:5], -1, 0
	v_writelane_b32 v253, s4, 51
	s_nop 1
	v_writelane_b32 v253, s5, 52
	s_lshl_b32 s4, s9, 2
	s_add_u32 s4, s16, s4
	s_addc_u32 s5, s17, 0
	s_add_u32 s6, s4, 0x1400
	s_addc_u32 s7, s5, 0
	v_writelane_b32 v253, s6, 53
	s_add_u32 s4, s4, 0x2400
	s_addc_u32 s5, s5, 0
	v_writelane_b32 v253, s7, 54
	v_writelane_b32 v253, s4, 55
	s_nop 1
	v_writelane_b32 v253, s5, 56
	s_add_u32 s4, s76, 0x43400
	s_addc_u32 s5, s77, 0
	v_writelane_b32 v253, s4, 57
	s_nop 1
	v_writelane_b32 v253, s5, 58
	s_add_u32 s4, s76, 0x43500
	s_addc_u32 s5, s77, 0
	v_writelane_b32 v253, s4, 59
	s_lshr_b32 s6, s25, 7
	s_bfe_u32 s7, s25, 0x10006
	v_writelane_b32 v253, s5, 60
	s_lshl_b32 s4, s34, 4
	s_and_b32 s28, s4, 0x3fffffe0
	s_lshl_b32 s4, s6, 14
	s_add_i32 s4, s4, 0
	v_writelane_b32 v253, s4, 61
	s_lshl_b32 s4, s2, 9
	v_writelane_b32 v253, s4, 62
	s_lshl_b32 s5, s7, 1
	s_lshl_b32 s4, s7, 6
	s_lshl_b32 s90, s7, 14
	s_add_i32 s29, 0, 0x20080
	s_and_b32 s8, 64, s25
	s_lshl_b32 s36, s82, 9
	s_cmp_eq_u32 s7, 0
	s_cselect_b64 s[12:13], -1, 0
	s_cmp_lg_u32 s8, 0
	v_writelane_b32 v253, s12, 63
	s_cselect_b64 s[8:9], -1, 0
	s_lshl_b32 s6, s6, 5
	v_writelane_b32 v254, s13, 0
	v_writelane_b32 v254, s8, 1
	s_cmpk_lt_i32 s2, 0x120
	v_lshl_add_u32 v203, v164, 2, s29
	v_writelane_b32 v254, s9, 2
	v_writelane_b32 v254, s6, 3
	s_cselect_b64 s[6:7], -1, 0
	v_writelane_b32 v254, s6, 4
	s_lshl_b32 s14, s2, 3
	s_add_i32 s16, s34, s14
	v_writelane_b32 v254, s7, 5
	s_lshr_b32 s6, s3, 29
	s_add_i32 s6, s2, s6
	s_ashr_i32 s30, s6, 3
	s_lshl_b32 s7, s2, 5
	s_mul_i32 s8, s30, 0xffffff01
	s_add_i32 s7, s8, s7
	s_ashr_i32 s8, s7, 31
	s_lshr_b32 s8, s8, 26
	s_add_i32 s8, s7, s8
	s_and_b32 s9, s8, 0xffffffc0
	s_sub_i32 s7, s7, s9
	s_bfe_i32 s9, s7, 0x80000
	s_bfe_u32 s9, s9, 0x3000c
	s_add_i32 s9, s7, s9
	s_and_b32 s12, s9, 0xf8
	s_sub_i32 s7, s7, s12
	s_ashr_i32 s8, s8, 6
	s_lshl_b32 s8, s8, 3
	s_sext_i32_i8 s7, s7
	s_add_i32 s8, s8, s7
	s_bfe_i32 s7, s9, 0x80000
	s_sext_i32_i16 s7, s7
	s_and_b32 s9, s2, 3
	s_lshl_b32 s14, s16, 6
	s_ashr_i32 s7, s7, 3
	s_bfe_u32 s12, s2, 0x30002
	s_lshl_b32 s13, s9, 10
	s_lshl_b32 s73, s82, 3
	v_writelane_b32 v254, s14, 6
	s_mov_b32 s14, s16
	v_writelane_b32 v254, s14, 7
	s_cmpk_lt_i32 s16, 0x800
	s_nop 0
	v_writelane_b32 v254, s15, 8
	s_cselect_b64 s[14:15], -1, 0
	v_writelane_b32 v254, s14, 9
	s_cmpk_lt_i32 s2, 0x420
	s_nop 0
	v_writelane_b32 v254, s15, 10
	s_cselect_b64 s[14:15], -1, 0
	s_and_b32 s6, s6, -8
	v_writelane_b32 v254, s14, 11
	s_sub_i32 s33, s2, s6
	s_nop 0
	v_writelane_b32 v254, s15, 12
	s_add_u32 s14, s46, 0x4000000
	s_addc_u32 s15, s47, 0
	v_readlane_b32 s40, v252, 0
	v_readlane_b32 s52, v252, 12
	v_readlane_b32 s53, v252, 13
	v_readlane_b32 s50, v252, 10
	v_readlane_b32 s51, v252, 11
	s_cmp_lg_u64 s[52:53], 0
	v_writelane_b32 v254, s14, 13
	s_cselect_b64 s[50:51], -1, 0
	s_cmpk_lt_i32 s2, 0x140
	v_writelane_b32 v254, s15, 14
	s_cselect_b64 s[14:15], -1, 0
	v_writelane_b32 v254, s14, 15
	s_bfe_u32 s6, s25, 0x30006
	s_lshl_b32 s17, s6, 8
	v_writelane_b32 v254, s15, 16
	s_and_b32 s14, s2, 7
	v_writelane_b32 v254, s17, 17
	s_lshl_b32 s17, s6, 2
	v_readlane_b32 s54, v252, 14
	v_readlane_b32 s55, v252, 15
	s_bfe_u32 s15, s2, 0x30003
	s_lshl_b32 s16, s14, 11
	v_writelane_b32 v254, s17, 18
	s_lshl_b32 s17, s6, 20
	s_mov_b64 s[54:55], s[22:23]
	s_add_u32 s22, s26, s17
	s_addc_u32 s23, s27, 0
	s_cmp_lt_i32 s33, 0
	s_movk_i32 s17, 0x85
	s_movk_i32 s17, 0x80
	s_mul_i32 s17, s33, s17
	v_writelane_b32 v254, s22, 19
	s_add_i32 s17, s17, s30
	s_add_i32 s22, s2, 0x320
	s_cmpk_ge_u32 s2, 0xe0
	s_cselect_b32 s17, s22, s17
	v_writelane_b32 v255, s54, 10
	v_writelane_b32 v254, s23, 20
	s_ashr_i32 s22, s17, 31
	s_lshr_b32 s22, s22, 24
	s_add_i32 s22, s17, s22
	s_and_b32 s23, s22, 0xffffff00
	s_ashr_i32 s22, s22, 8
	s_lshl_b32 s22, s22, 3
	s_sub_i32 s17, s17, s23
	s_sub_i32 s23, 33, s22
	s_min_i32 s23, s23, 8
	v_writelane_b32 v254, s33, 21
	s_cmpk_lt_i32 s2, 0x100
	v_writelane_b32 v254, s30, 22
	s_cselect_b32 s88, 0, s13
	v_writelane_b32 v254, s88, 23
	s_cselect_b32 s12, s7, s12
	s_cselect_b32 s7, s7, s15
	v_writelane_b32 v254, s89, 24
	v_writelane_b32 v254, s12, 25
	v_writelane_b32 v254, s7, 26
	s_cselect_b32 s7, s8, 32
	v_writelane_b32 v254, s7, 27
	s_cselect_b32 s7, -1, s9
	v_writelane_b32 v254, s7, 28
	s_cselect_b32 s7, -1, s14
	v_writelane_b32 v254, s7, 29
	s_cselect_b32 s7, 32, 8
	v_writelane_b32 v254, s7, 30
	s_cselect_b32 s7, 0x80, 16
	v_writelane_b32 v254, s7, 31
	s_sext_i32_i16 s7, s23
	v_cvt_f32_i32_e32 v0, s7
	v_cvt_f32_i32_e32 v1, s17
	s_cselect_b32 s88, 0, s16
	s_lshl_b32 s6, s6, 21
	v_rcp_iflag_f32_e32 v2, v0
	s_add_u32 s8, s26, s6
	v_writelane_b32 v254, s26, 32
	s_addc_u32 s9, s27, 0
	v_mul_f32_e32 v2, v1, v2
	v_writelane_b32 v254, s27, 33
	s_xor_b32 s6, s17, s7
	v_trunc_f32_e32 v2, v2
	v_writelane_b32 v254, s8, 34
	s_ashr_i32 s6, s6, 30
	v_fma_f32 v1, -v2, v0, v1
	v_writelane_b32 v254, s9, 35
	s_or_b32 s8, s6, 1
	v_cmp_ge_f32_e64 s[6:7], |v1|, |v0|
	v_cvt_i32_f32_e32 v0, v2
	s_and_b64 s[6:7], s[6:7], exec
	s_mul_i32 s6, s83, s82
	s_mul_i32 s6, s6, s24
	v_writelane_b32 v254, s6, 36
	s_cselect_b32 s6, s8, 0
	v_readfirstlane_b32 s7, v0
	s_add_i32 s6, s7, s6
	s_mul_i32 s7, s6, s23
	s_sub_i32 s7, s17, s7
	s_sext_i32_i16 s7, s7
	s_add_i32 s7, s22, s7
	v_writelane_b32 v254, s7, 37
	v_writelane_b32 v254, s29, 38
	s_sext_i32_i16 s6, s6
	v_writelane_b32 v254, s6, 39
	s_lshl_b32 s6, s34, 7
	v_writelane_b32 v254, s6, 40
	s_add_u32 s6, s76, 0x1a740000
	s_addc_u32 s7, s77, 0
	v_writelane_b32 v254, s6, 41
	s_lshl_b32 s5, s5, 2
	s_lshl_b32 s4, s4, 1
	v_writelane_b32 v254, s7, 42
	v_writelane_b32 v254, s5, 43
	v_writelane_b32 v254, s28, 44
	s_add_i32 s5, s28, 0x800
	v_writelane_b32 v254, s5, 45
	s_add_i32 s5, 0, 0x20040
	v_writelane_b32 v254, s5, 46
	s_add_i32 s5, 0, 0x20044
	v_writelane_b32 v254, s5, 47
	v_writelane_b32 v254, s4, 48
	v_cmp_gt_u32_e64 s[6:7], 3, v164
	s_ashr_i32 s37, s36, 31
	v_writelane_b32 v254, s5, 49
	s_add_i32 s4, 0, 0x20084
	v_writelane_b32 v254, s4, 50
	v_writelane_b32 v254, s6, 51
	s_lshl_b64 s[64:65], s[36:37], 4
	v_writelane_b32 v255, s55, 11
	v_writelane_b32 v254, s7, 52
	v_writelane_b32 v254, s88, 53
	s_lshl_b64 s[6:7], s[36:37], 7
	v_xor_b32_e32 v0, v165, v164
	v_writelane_b32 v254, s89, 54
	v_writelane_b32 v254, s6, 55
	v_writelane_b32 v255, s64, 12
	v_lshlrev_b32_e32 v1, 3, v0
	v_writelane_b32 v254, s7, 56
	s_mov_b64 s[6:7], -1
	v_writelane_b32 v254, s6, 57
	s_lshl_b64 s[92:93], s[36:37], 2
	v_writelane_b32 v255, s65, 13
	v_writelane_b32 v254, s7, 58
	v_writelane_b32 v254, s72, 59
	v_writelane_b32 v254, s73, 60
	v_writelane_b32 v254, s86, 61
	v_and_b32_e32 v2, 56, v1
	v_mov_b32_e32 v0, 0
	v_and_b32_e32 v4, 0x78, v1
	v_writelane_b32 v254, s87, 62
	v_writelane_b32 v255, s92, 14
	v_mov_b32_e32 v113, v0
	v_mov_b32_e32 v114, v0
	v_mov_b32_e32 v115, v0
	v_lshlrev_b32_e32 v166, 1, v4
	v_lshlrev_b32_e32 v168, 1, v2
	s_mov_b32 s83, 0xffff0000
	s_mov_b32 s12, 0x800000
	s_movk_i32 s13, 0x4400
	s_add_i32 s33, 0, 0x20000
	s_mov_b32 s22, 0x40000
	s_movk_i32 s23, 0x7fff
	s_mov_b32 s24, 0x80000
	s_mov_b32 s25, 0xc0000
	s_mov_b32 s29, 0x100000
	s_mov_b32 s14, 0x140000
	s_mov_b32 s15, 0x180000
	s_mov_b32 s28, 0x1c0000
	s_mov_b32 s30, 0x3e38aa3b
	s_mov_b32 s52, 0xf149f2ca
	s_mov_b32 s53, 0xc2800000
	s_mov_b64 s[4:5], 0
	s_mov_b64 s[26:27], 0x80
	s_mov_b32 s66, s89
	v_writelane_b32 v254, s74, 63
	v_writelane_b32 v255, s93, 15
	v_readlane_b32 s41, v252, 1
	v_readlane_b32 s42, v252, 2
	v_readlane_b32 s43, v252, 3
	v_readlane_b32 s44, v252, 4
	v_readlane_b32 s45, v252, 5
	v_readlane_b32 s46, v252, 6
	v_readlane_b32 s47, v252, 7
	v_readlane_b32 s48, v252, 8
	v_readlane_b32 s49, v252, 9
	s_branch .LBB0_63

.LBB0_702:
	v_lshrrev_b32_e32 v18, 1, v16
	v_and_b32_e32 v18, 24, v18
	v_and_b32_e32 v17, 15, v16
	v_lshlrev_b32_e32 v19, 1, v18
	v_lshlrev_b32_e32 v16, 2, v16
	v_lshl_or_b32 v1, s6, 6, v17
	v_lshl_or_b32 v17, v17, 6, v19
	s_lshl_b32 s6, s6, 13
	v_and_b32_e32 v16, 32, v16
	v_bitop3_b32 v19, v17, s6, v16 bitop3:0xde
	s_lshl_b32 s6, s7, 5
	s_and_b32 s41, s6, 0x60
	s_lshl_b32 s6, s41, 7
	v_bitop3_b32 v152, v17, s6, v16 bitop3:0xde
	s_lshl_b32 s6, s37, 2
	v_readlane_b32 s7, v252, 16
	s_add_u32 s6, s7, s6
	v_readlane_b32 s7, v252, 17
	s_addc_u32 s7, s7, 0
	s_add_i32 m0, s57, 0x18000
	v_lshl_add_u64 v[8:9], v[8:9], 0, s[26:27]
	s_waitcnt vmcnt(2)
	s_barrier
	global_load_lds_dwordx4 v[8:9], off
	v_lshl_add_u64 v[6:7], v[6:7], 0, s[26:27]
	s_add_i32 m0, s57, 0x1a000
	s_add_i32 s37, s57, 0x8000
	s_add_i32 s61, s57, 0xa000
	global_load_lds_dwordx4 v[6:7], off
	v_lshl_add_u64 v[2:3], v[2:3], 0, s[26:27]
	s_mov_b32 m0, s37
	s_add_u32 s38, s8, 0x80080
	global_load_lds_dwordx4 v[2:3], off
	v_lshl_add_u64 v[2:3], v[4:5], 0, s[26:27]
	s_mov_b32 m0, s61
	s_addc_u32 s39, s9, 0
	global_load_lds_dwordx4 v[2:3], off
	s_add_i32 m0, s57, 0x1c000
	v_lshl_add_u64 v[2:3], s[38:39], 0, v[136:137]
	global_load_lds_dwordx4 v[2:3], off
	v_lshl_add_u64 v[2:3], s[38:39], 0, v[140:141]
	s_add_i32 m0, s57, 0x1e000
	s_cmpk_lt_u32 s16, 0x100
	global_load_lds_dwordx4 v[2:3], off
	v_lshlrev_b32_e32 v2, 15, v10
	v_and_b32_e32 v2, 0xffff0000, v2
	v_lshl_add_u32 v2, v11, 12, v2
	v_and_b32_e32 v3, 1, v10
	v_lshl_or_b32 v2, v3, 6, v2
	v_lshl_add_u32 v142, v12, 1, v2
	v_lshlrev_b32_e32 v2, 15, v13
	v_and_b32_e32 v2, 0xffff0000, v2
	s_waitcnt vmcnt(6)
	v_lshl_add_u32 v2, v14, 12, v2
	v_and_b32_e32 v3, 1, v13
	v_lshl_or_b32 v2, v3, 6, v2
	s_cselect_b64 s[16:17], -1, 0
	v_or_b32_e32 v153, s41, v18
	v_mov_b32_e32 v143, v0
	v_lshl_add_u32 v144, v15, 1, v2
	v_mov_b32_e32 v145, v0
	s_mov_b32 s62, 0
	s_mov_b32 s98, 0
	v_add_u32_e32 v154, 0, v19
	s_movk_i32 s71, 0x85
	s_barrier
	s_branch .LBB0_705

.LBB0_704:
	s_andn2_b64 vcc, exec, s[8:9]
	s_mov_b32 s40, s42
	s_mov_b32 s84, s44
	s_mov_b32 s98, s99
	s_mov_b64 s[8:9], s[48:49]
	s_mov_b64 s[86:87], s[46:47]
	s_cbranch_vccz .LBB0_746
.LBB0_705:
	s_add_i32 s62, s62, 1
	s_mul_i32 s38, s62, s31
	s_mul_hi_u32 s39, s62, s82
	s_add_i32 s39, s39, s38
	s_mul_i32 s38, s62, s82
	s_add_u32 s46, s38, s2
	s_addc_u32 s47, s39, s3
	v_cmp_gt_i64_e32 vcc, s[46:47], v[178:179]
	v_cmp_lt_i64_e64 s[38:39], s[46:47], v[176:177]
	s_cbranch_vccnz .LBB0_707
	s_mov_b32 s99, 0
	s_cmpk_lt_i32 s46, 0x400
	s_cbranch_scc1 .Lmy_ht_full
	s_sub_i32 s99, s46, 0x400
	s_lshr_b32 s46, s99, 1
	s_add_i32 s46, s46, 0x400
	s_and_b32 s99, s99, 1
	s_sub_i32 s99, 2, s99
.Lmy_ht_full:
	s_sub_i32 s46, s46, 32
	s_ashr_i32 s41, s46, 31
	s_lshr_b32 s41, s41, 29
	s_add_i32 s41, s46, s41
	s_ashr_i32 s42, s41, 3
	s_and_b32 s41, s41, -8
	s_sub_i32 s41, s46, s41
	s_cmp_lt_i32 s41, 0
	s_movk_i32 s43, 0x80
	s_mul_i32 s41, s41, s43
	s_add_i32 s41, s41, s42
	s_ashr_i32 s42, s41, 31
	s_lshr_b32 s42, s42, 24
	s_add_i32 s42, s41, s42
	s_ashr_i32 s43, s42, 8
	s_lshl_b32 s43, s43, 3
	s_sub_i32 s44, 33, s43
	s_min_i32 s44, s44, 8
	s_abs_i32 s45, s44
	v_cvt_f32_u32_e32 v2, s45
	s_sub_i32 s47, 0, s45
	s_and_b32 s42, s42, 0xffffff00
	s_sub_i32 s41, s41, s42
	v_rcp_iflag_f32_e32 v2, v2
	s_abs_i32 s42, s41
	s_xor_b32 s46, s41, s44
	s_ashr_i32 s46, s46, 31
	v_mul_f32_e32 v2, 0x4f7ffffe, v2
	v_cvt_u32_f32_e32 v2, v2
	s_nop 0
	v_readfirstlane_b32 s48, v2
	s_mul_i32 s47, s47, s48
	s_mul_hi_u32 s47, s48, s47
	s_add_i32 s48, s48, s47
	s_mul_hi_u32 s47, s42, s48
	s_mul_i32 s48, s47, s45
	s_sub_i32 s42, s42, s48
	s_add_i32 s49, s47, 1
	s_sub_i32 s48, s42, s45
	s_cmp_ge_u32 s42, s45
	s_cselect_b32 s47, s49, s47
	s_cselect_b32 s42, s48, s42
	s_add_i32 s48, s47, 1
	s_cmp_ge_u32 s42, s45
	s_cselect_b32 s42, s48, s47
	s_xor_b32 s42, s42, s46
	s_sub_i32 s42, s42, s46
	s_mul_i32 s44, s42, s44
	s_sub_i32 s41, s41, s44
	s_add_i32 s44, s41, s43

.LBB0_715:
	v_fmamk_f32 v155, v155, 0x3a000000, v205
	v_cmp_gt_f32_e32 vcc, s12, v155
	v_mul_f32_e32 v156, 0x4b800000, v155
	v_lshl_or_b32 v148, s40, 8, v153
	v_cndmask_b32_e32 v155, v155, v156, vcc
	v_rsq_f32_e32 v155, v155
	v_lshlrev_b64 v[158:159], 14, v[146:147]
	v_ashrrev_i32_e32 v149, 31, v148
	v_lshl_add_u64 v[158:159], s[10:11], 0, v[158:159]
	v_mul_f32_e32 v156, 0x45800000, v155
	v_cndmask_b32_e32 v156, v155, v156, vcc
	v_pk_mul_f32 v[128:129], v[128:129], v[156:157] op_sel_hi:[1,0]
	v_pk_mul_f32 v[132:133], v[132:133], v[156:157] op_sel_hi:[1,0]
	v_pk_mul_f32 v[130:131], v[130:131], v[156:157] op_sel_hi:[1,0]
	v_max_f32_e32 v128, 0, v128
	v_pk_mul_f32 v[134:135], v[134:135], v[156:157] op_sel_hi:[1,0]
	v_mul_f32_e32 v147, v128, v128
	v_max_f32_e32 v128, 0, v133
	v_max_f32_e32 v129, 0, v129
	v_max_f32_e32 v130, 0, v130
	v_max_f32_e32 v132, 0, v132
	v_mul_f32_e32 v128, v128, v128
	v_mul_f32_e32 v133, v129, v129
	v_max_f32_e32 v129, 0, v134
	v_mul_f32_e32 v134, v130, v130
	v_max_f32_e32 v130, 0, v135
	v_max_f32_e32 v131, 0, v131
	v_pk_mul_f32 v[120:121], v[120:121], v[156:157] op_sel_hi:[1,0]
	v_lshl_add_u64 v[158:159], v[148:149], 1, v[158:159]
	v_mul_f32_e32 v132, v132, v132
	v_mul_f32_e32 v129, v129, v129
	v_mul_f32_e32 v130, v130, v130
	v_mul_f32_e32 v131, v131, v131
	v_cvt_pk_bf16_f32 v128, v132, v128
	v_pk_mul_f32 v[124:125], v[124:125], v[156:157] op_sel_hi:[1,0]
	v_pk_mul_f32 v[122:123], v[122:123], v[156:157] op_sel_hi:[1,0]
	v_max_f32_e32 v120, 0, v120
	v_cvt_pk_bf16_f32 v129, v129, v130
	v_cvt_pk_bf16_f32 v130, v147, v133
	v_cvt_pk_bf16_f32 v131, v134, v131
	s_bitcmp1_b32 s98, 0
	s_cbranch_scc1 .Lmy_hs_0
	global_store_dwordx4 v[158:159], v[128:131], off
.Lmy_hs_0:
	v_pk_mul_f32 v[126:127], v[126:127], v[156:157] op_sel_hi:[1,0]
	v_max_f32_e32 v121, 0, v121
	v_mul_f32_e32 v128, v120, v120
	v_max_f32_e32 v120, 0, v125
	v_max_f32_e32 v122, 0, v122
	v_max_f32_e32 v124, 0, v124
	v_mul_f32_e32 v120, v120, v120
	v_mul_f32_e32 v125, v121, v121
	v_max_f32_e32 v121, 0, v126
	v_mul_f32_e32 v126, v122, v122
	v_max_f32_e32 v122, 0, v127
	v_max_f32_e32 v123, 0, v123
	v_mul_f32_e32 v124, v124, v124
	v_mul_f32_e32 v121, v121, v121
	v_mul_f32_e32 v122, v122, v122
	v_mul_f32_e32 v123, v123, v123
	v_cvt_pk_bf16_f32 v120, v124, v120
	v_cvt_pk_bf16_f32 v121, v121, v122
	v_cvt_pk_bf16_f32 v122, v128, v125
	v_cvt_pk_bf16_f32 v123, v126, v123
	s_bitcmp1_b32 s98, 0
	s_cbranch_scc1 .Lmy_hs_1
	global_store_dwordx4 v[158:159], v[120:123], off offset:256
.Lmy_hs_1:
	v_readlane_b32 s92, v255, 14
	s_mov_b64 s[84:85], -1
	v_cndmask_b32_e64 v120, 0, 1, s[8:9]
	v_cmp_ne_u32_e64 s[40:41], 1, v120
	s_andn2_b64 vcc, exec, s[8:9]
	v_readlane_b32 s93, v255, 15
	s_cbranch_vccnz .LBB0_717
	s_nop 1
	v_mov_b32_e32 v122, v215
	s_mov_b64 s[84:85], 0

.LBB0_719:
	v_fmamk_f32 v122, v122, 0x3a000000, v205
	v_mul_f32_e32 v123, 0x4b800000, v122
	v_cmp_gt_f32_e32 vcc, s12, v122
	v_lshlrev_b64 v[120:121], 14, v[120:121]
	v_lshl_add_u64 v[120:121], s[10:11], 0, v[120:121]
	v_cndmask_b32_e32 v122, v122, v123, vcc
	v_rsq_f32_e32 v122, v122
	v_lshl_add_u64 v[120:121], v[148:149], 1, v[120:121]
	s_mov_b64 s[8:9], -1
	v_mul_f32_e32 v123, 0x45800000, v122
	v_cndmask_b32_e32 v122, v122, v123, vcc
	v_pk_mul_f32 v[106:107], v[106:107], v[122:123] op_sel_hi:[1,0]
	v_pk_mul_f32 v[116:117], v[116:117], v[122:123] op_sel_hi:[1,0]
	v_pk_mul_f32 v[108:109], v[108:109], v[122:123] op_sel_hi:[1,0]
	v_max_f32_e32 v106, 0, v106
	v_pk_mul_f32 v[118:119], v[118:119], v[122:123] op_sel_hi:[1,0]
	v_mul_f32_e32 v123, v106, v106
	v_max_f32_e32 v106, 0, v117
	v_max_f32_e32 v107, 0, v107
	v_max_f32_e32 v108, 0, v108
	v_max_f32_e32 v116, 0, v116
	v_mul_f32_e32 v106, v106, v106
	v_mul_f32_e32 v117, v107, v107
	v_max_f32_e32 v107, 0, v118
	v_mul_f32_e32 v118, v108, v108
	v_max_f32_e32 v108, 0, v119
	v_max_f32_e32 v109, 0, v109
	v_pk_mul_f32 v[100:101], v[100:101], v[122:123] op_sel_hi:[1,0]
	v_pk_mul_f32 v[98:99], v[98:99], v[122:123] op_sel_hi:[1,0]
	v_mul_f32_e32 v116, v116, v116
	v_mul_f32_e32 v107, v107, v107
	v_mul_f32_e32 v108, v108, v108
	v_mul_f32_e32 v109, v109, v109
	v_cvt_pk_bf16_f32 v106, v116, v106
	v_pk_mul_f32 v[104:105], v[104:105], v[122:123] op_sel_hi:[1,0]
	v_pk_mul_f32 v[102:103], v[102:103], v[122:123] op_sel_hi:[1,0]
	v_max_f32_e32 v98, 0, v98
	v_max_f32_e32 v99, 0, v99
	v_max_f32_e32 v100, 0, v100
	v_cvt_pk_bf16_f32 v107, v107, v108
	v_cvt_pk_bf16_f32 v108, v123, v117
	v_cvt_pk_bf16_f32 v109, v118, v109
	s_bitcmp1_b32 s98, 0
	s_cbranch_scc1 .Lmy_hs_2
	global_store_dwordx4 v[120:121], v[106:109], off
.Lmy_hs_2:
	v_max_f32_e32 v102, 0, v102
	v_max_f32_e32 v101, 0, v101
	v_mul_f32_e32 v106, v98, v98
	v_max_f32_e32 v98, 0, v103
	v_mul_f32_e32 v103, v99, v99
	v_max_f32_e32 v99, 0, v104
	v_mul_f32_e32 v104, v100, v100
	v_max_f32_e32 v100, 0, v105
	v_mul_f32_e32 v98, v98, v98
	v_mul_f32_e32 v99, v99, v99
	v_mul_f32_e32 v100, v100, v100
	v_mul_f32_e32 v102, v102, v102
	v_mul_f32_e32 v101, v101, v101
	v_cvt_pk_bf16_f32 v98, v102, v98
	v_cvt_pk_bf16_f32 v99, v99, v100
	v_cvt_pk_bf16_f32 v100, v106, v103
	s_and_b64 vcc, exec, s[40:41]
	v_cvt_pk_bf16_f32 v101, v104, v101
	s_bitcmp1_b32 s98, 0
	s_cbranch_scc1 .Lmy_hs_3
	global_store_dwordx4 v[120:121], v[98:101], off offset:256
.Lmy_hs_3:
	s_cbranch_vccnz .LBB0_721
	s_nop 1
	v_mov_b32_e32 v100, v216
	s_mov_b64 s[8:9], 0

.LBB0_723:
	v_fmamk_f32 v100, v100, 0x3a000000, v205
	v_mul_f32_e32 v101, 0x4b800000, v100
	v_cmp_gt_f32_e32 vcc, s12, v100
	v_lshlrev_b64 v[98:99], 14, v[98:99]
	v_lshl_add_u64 v[98:99], s[10:11], 0, v[98:99]
	v_cndmask_b32_e32 v100, v100, v101, vcc
	v_rsq_f32_e32 v100, v100
	v_lshl_add_u64 v[98:99], v[148:149], 1, v[98:99]
	s_mov_b64 s[8:9], -1
	v_mul_f32_e32 v101, 0x45800000, v100
	v_cndmask_b32_e32 v100, v100, v101, vcc
	v_pk_mul_f32 v[90:91], v[90:91], v[100:101] op_sel_hi:[1,0]
	v_pk_mul_f32 v[94:95], v[94:95], v[100:101] op_sel_hi:[1,0]
	v_pk_mul_f32 v[92:93], v[92:93], v[100:101] op_sel_hi:[1,0]
	v_max_f32_e32 v90, 0, v90
	v_pk_mul_f32 v[96:97], v[96:97], v[100:101] op_sel_hi:[1,0]
	v_mul_f32_e32 v101, v90, v90
	v_max_f32_e32 v90, 0, v95
	v_max_f32_e32 v91, 0, v91
	v_max_f32_e32 v92, 0, v92
	v_max_f32_e32 v94, 0, v94
	v_mul_f32_e32 v90, v90, v90
	v_mul_f32_e32 v95, v91, v91
	v_max_f32_e32 v91, 0, v96
	v_mul_f32_e32 v96, v92, v92
	v_max_f32_e32 v92, 0, v97
	v_max_f32_e32 v93, 0, v93
	v_pk_mul_f32 v[84:85], v[84:85], v[100:101] op_sel_hi:[1,0]
	v_pk_mul_f32 v[82:83], v[82:83], v[100:101] op_sel_hi:[1,0]
	v_mul_f32_e32 v94, v94, v94
	v_mul_f32_e32 v91, v91, v91
	v_mul_f32_e32 v92, v92, v92
	v_mul_f32_e32 v93, v93, v93
	v_cvt_pk_bf16_f32 v90, v94, v90
	v_pk_mul_f32 v[88:89], v[88:89], v[100:101] op_sel_hi:[1,0]
	v_pk_mul_f32 v[86:87], v[86:87], v[100:101] op_sel_hi:[1,0]
	v_max_f32_e32 v82, 0, v82
	v_max_f32_e32 v83, 0, v83
	v_max_f32_e32 v84, 0, v84
	v_cvt_pk_bf16_f32 v91, v91, v92
	v_cvt_pk_bf16_f32 v92, v101, v95
	v_cvt_pk_bf16_f32 v93, v96, v93
	s_bitcmp1_b32 s98, 0
	s_cbranch_scc1 .Lmy_hs_4
	global_store_dwordx4 v[98:99], v[90:93], off
.Lmy_hs_4:
	v_max_f32_e32 v86, 0, v86
	v_max_f32_e32 v85, 0, v85
	v_mul_f32_e32 v90, v82, v82
	v_max_f32_e32 v82, 0, v87
	v_mul_f32_e32 v87, v83, v83
	v_max_f32_e32 v83, 0, v88
	v_mul_f32_e32 v88, v84, v84
	v_max_f32_e32 v84, 0, v89
	v_mul_f32_e32 v82, v82, v82
	v_mul_f32_e32 v83, v83, v83
	v_mul_f32_e32 v84, v84, v84
	v_mul_f32_e32 v86, v86, v86
	v_mul_f32_e32 v85, v85, v85
	v_cvt_pk_bf16_f32 v82, v86, v82
	v_cvt_pk_bf16_f32 v83, v83, v84
	v_cvt_pk_bf16_f32 v84, v90, v87
	s_and_b64 vcc, exec, s[40:41]
	v_cvt_pk_bf16_f32 v85, v88, v85
	s_bitcmp1_b32 s98, 0
	s_cbranch_scc1 .Lmy_hs_5
	global_store_dwordx4 v[98:99], v[82:85], off offset:256
.Lmy_hs_5:
	s_cbranch_vccnz .LBB0_725
	s_nop 1
	v_mov_b32_e32 v84, v217
	s_mov_b64 s[8:9], 0

.LBB0_727:
	v_fmamk_f32 v84, v84, 0x3a000000, v205
	v_mul_f32_e32 v85, 0x4b800000, v84
	v_cmp_gt_f32_e32 vcc, s12, v84
	v_lshlrev_b64 v[82:83], 14, v[82:83]
	v_lshl_add_u64 v[82:83], s[10:11], 0, v[82:83]
	v_cndmask_b32_e32 v84, v84, v85, vcc
	v_rsq_f32_e32 v84, v84
	v_lshl_add_u64 v[82:83], v[148:149], 1, v[82:83]
	s_mov_b64 s[8:9], -1
	v_mul_f32_e32 v85, 0x45800000, v84
	v_cndmask_b32_e32 v84, v84, v85, vcc
	v_pk_mul_f32 v[74:75], v[74:75], v[84:85] op_sel_hi:[1,0]
	v_pk_mul_f32 v[78:79], v[78:79], v[84:85] op_sel_hi:[1,0]
	v_pk_mul_f32 v[76:77], v[76:77], v[84:85] op_sel_hi:[1,0]
	v_max_f32_e32 v74, 0, v74
	v_pk_mul_f32 v[80:81], v[80:81], v[84:85] op_sel_hi:[1,0]
	v_mul_f32_e32 v85, v74, v74
	v_max_f32_e32 v74, 0, v79
	v_max_f32_e32 v75, 0, v75
	v_max_f32_e32 v76, 0, v76
	v_max_f32_e32 v78, 0, v78
	v_mul_f32_e32 v74, v74, v74
	v_mul_f32_e32 v79, v75, v75
	v_max_f32_e32 v75, 0, v80
	v_mul_f32_e32 v80, v76, v76
	v_max_f32_e32 v76, 0, v81
	v_max_f32_e32 v77, 0, v77
	v_pk_mul_f32 v[68:69], v[68:69], v[84:85] op_sel_hi:[1,0]
	v_pk_mul_f32 v[66:67], v[66:67], v[84:85] op_sel_hi:[1,0]
	v_mul_f32_e32 v78, v78, v78
	v_mul_f32_e32 v75, v75, v75
	v_mul_f32_e32 v76, v76, v76
	v_mul_f32_e32 v77, v77, v77
	v_cvt_pk_bf16_f32 v74, v78, v74
	v_pk_mul_f32 v[72:73], v[72:73], v[84:85] op_sel_hi:[1,0]
	v_pk_mul_f32 v[70:71], v[70:71], v[84:85] op_sel_hi:[1,0]
	v_max_f32_e32 v66, 0, v66
	v_max_f32_e32 v67, 0, v67
	v_max_f32_e32 v68, 0, v68
	v_cvt_pk_bf16_f32 v75, v75, v76
	v_cvt_pk_bf16_f32 v76, v85, v79
	v_cvt_pk_bf16_f32 v77, v80, v77
	s_bitcmp1_b32 s98, 0
	s_cbranch_scc1 .Lmy_hs_6
	global_store_dwordx4 v[82:83], v[74:77], off
.Lmy_hs_6:
	v_max_f32_e32 v70, 0, v70
	v_max_f32_e32 v69, 0, v69
	v_mul_f32_e32 v74, v66, v66
	v_max_f32_e32 v66, 0, v71
	v_mul_f32_e32 v71, v67, v67
	v_max_f32_e32 v67, 0, v72
	v_mul_f32_e32 v72, v68, v68
	v_max_f32_e32 v68, 0, v73
	v_mul_f32_e32 v66, v66, v66
	v_mul_f32_e32 v67, v67, v67
	v_mul_f32_e32 v68, v68, v68
	v_mul_f32_e32 v70, v70, v70
	v_mul_f32_e32 v69, v69, v69
	v_cvt_pk_bf16_f32 v66, v70, v66
	v_cvt_pk_bf16_f32 v67, v67, v68
	v_cvt_pk_bf16_f32 v68, v74, v71
	s_and_b64 vcc, exec, s[40:41]
	v_cvt_pk_bf16_f32 v69, v72, v69
	s_bitcmp1_b32 s98, 0
	s_cbranch_scc1 .Lmy_hs_7
	global_store_dwordx4 v[82:83], v[66:69], off offset:256
.Lmy_hs_7:
	s_cbranch_vccnz .LBB0_729
	s_nop 1
	v_mov_b32_e32 v68, v218
	s_mov_b64 s[8:9], 0

.LBB0_731:
	v_fmamk_f32 v68, v68, 0x3a000000, v205
	v_mul_f32_e32 v69, 0x4b800000, v68
	v_cmp_gt_f32_e32 vcc, s12, v68
	v_lshlrev_b64 v[66:67], 14, v[66:67]
	v_lshl_add_u64 v[66:67], s[10:11], 0, v[66:67]
	v_cndmask_b32_e32 v68, v68, v69, vcc
	v_rsq_f32_e32 v68, v68
	v_lshl_add_u64 v[66:67], v[148:149], 1, v[66:67]
	s_mov_b64 s[8:9], -1
	v_mul_f32_e32 v69, 0x45800000, v68
	v_cndmask_b32_e32 v68, v68, v69, vcc
	v_pk_mul_f32 v[58:59], v[58:59], v[68:69] op_sel_hi:[1,0]
	v_pk_mul_f32 v[62:63], v[62:63], v[68:69] op_sel_hi:[1,0]
	v_pk_mul_f32 v[60:61], v[60:61], v[68:69] op_sel_hi:[1,0]
	v_max_f32_e32 v58, 0, v58
	v_pk_mul_f32 v[64:65], v[64:65], v[68:69] op_sel_hi:[1,0]
	v_mul_f32_e32 v69, v58, v58
	v_max_f32_e32 v58, 0, v63
	v_max_f32_e32 v59, 0, v59
	v_max_f32_e32 v60, 0, v60
	v_max_f32_e32 v62, 0, v62
	v_mul_f32_e32 v58, v58, v58
	v_mul_f32_e32 v63, v59, v59
	v_max_f32_e32 v59, 0, v64
	v_mul_f32_e32 v64, v60, v60
	v_max_f32_e32 v60, 0, v65
	v_max_f32_e32 v61, 0, v61
	v_pk_mul_f32 v[52:53], v[52:53], v[68:69] op_sel_hi:[1,0]
	v_pk_mul_f32 v[50:51], v[50:51], v[68:69] op_sel_hi:[1,0]
	v_mul_f32_e32 v62, v62, v62
	v_mul_f32_e32 v59, v59, v59
	v_mul_f32_e32 v60, v60, v60
	v_mul_f32_e32 v61, v61, v61
	v_cvt_pk_bf16_f32 v58, v62, v58
	v_pk_mul_f32 v[56:57], v[56:57], v[68:69] op_sel_hi:[1,0]
	v_pk_mul_f32 v[54:55], v[54:55], v[68:69] op_sel_hi:[1,0]
	v_max_f32_e32 v50, 0, v50
	v_max_f32_e32 v51, 0, v51
	v_max_f32_e32 v52, 0, v52
	v_cvt_pk_bf16_f32 v59, v59, v60
	v_cvt_pk_bf16_f32 v60, v69, v63
	v_cvt_pk_bf16_f32 v61, v64, v61
	s_bitcmp1_b32 s98, 1
	s_cbranch_scc1 .Lmy_hs_8
	global_store_dwordx4 v[66:67], v[58:61], off
.Lmy_hs_8:
	v_max_f32_e32 v54, 0, v54
	v_max_f32_e32 v53, 0, v53
	v_mul_f32_e32 v58, v50, v50
	v_max_f32_e32 v50, 0, v55
	v_mul_f32_e32 v55, v51, v51
	v_max_f32_e32 v51, 0, v56
	v_mul_f32_e32 v56, v52, v52
	v_max_f32_e32 v52, 0, v57
	v_mul_f32_e32 v50, v50, v50
	v_mul_f32_e32 v51, v51, v51
	v_mul_f32_e32 v52, v52, v52
	v_mul_f32_e32 v54, v54, v54
	v_mul_f32_e32 v53, v53, v53
	v_cvt_pk_bf16_f32 v50, v54, v50
	v_cvt_pk_bf16_f32 v51, v51, v52
	v_cvt_pk_bf16_f32 v52, v58, v55
	s_and_b64 vcc, exec, s[40:41]
	v_cvt_pk_bf16_f32 v53, v56, v53
	s_bitcmp1_b32 s98, 1
	s_cbranch_scc1 .Lmy_hs_9
	global_store_dwordx4 v[66:67], v[50:53], off offset:256
.Lmy_hs_9:
	s_cbranch_vccnz .LBB0_733
	s_nop 1
	v_mov_b32_e32 v52, v219
	s_mov_b64 s[8:9], 0

.LBB0_735:
	v_fmamk_f32 v52, v52, 0x3a000000, v205
	v_mul_f32_e32 v53, 0x4b800000, v52
	v_cmp_gt_f32_e32 vcc, s12, v52
	v_lshlrev_b64 v[50:51], 14, v[50:51]
	v_lshl_add_u64 v[50:51], s[10:11], 0, v[50:51]
	v_cndmask_b32_e32 v52, v52, v53, vcc
	v_rsq_f32_e32 v52, v52
	v_lshl_add_u64 v[50:51], v[148:149], 1, v[50:51]
	s_mov_b64 s[8:9], -1
	v_mul_f32_e32 v53, 0x45800000, v52
	v_cndmask_b32_e32 v52, v52, v53, vcc
	v_pk_mul_f32 v[42:43], v[42:43], v[52:53] op_sel_hi:[1,0]
	v_pk_mul_f32 v[46:47], v[46:47], v[52:53] op_sel_hi:[1,0]
	v_pk_mul_f32 v[44:45], v[44:45], v[52:53] op_sel_hi:[1,0]
	v_max_f32_e32 v42, 0, v42
	v_pk_mul_f32 v[48:49], v[48:49], v[52:53] op_sel_hi:[1,0]
	v_mul_f32_e32 v53, v42, v42
	v_max_f32_e32 v42, 0, v47
	v_max_f32_e32 v43, 0, v43
	v_max_f32_e32 v44, 0, v44
	v_max_f32_e32 v46, 0, v46
	v_mul_f32_e32 v42, v42, v42
	v_mul_f32_e32 v47, v43, v43
	v_max_f32_e32 v43, 0, v48
	v_mul_f32_e32 v48, v44, v44
	v_max_f32_e32 v44, 0, v49
	v_max_f32_e32 v45, 0, v45
	v_pk_mul_f32 v[36:37], v[36:37], v[52:53] op_sel_hi:[1,0]
	v_pk_mul_f32 v[34:35], v[34:35], v[52:53] op_sel_hi:[1,0]
	v_mul_f32_e32 v46, v46, v46
	v_mul_f32_e32 v43, v43, v43
	v_mul_f32_e32 v44, v44, v44
	v_mul_f32_e32 v45, v45, v45
	v_cvt_pk_bf16_f32 v42, v46, v42
	v_pk_mul_f32 v[40:41], v[40:41], v[52:53] op_sel_hi:[1,0]
	v_pk_mul_f32 v[38:39], v[38:39], v[52:53] op_sel_hi:[1,0]
	v_max_f32_e32 v34, 0, v34
	v_max_f32_e32 v35, 0, v35
	v_max_f32_e32 v36, 0, v36
	v_cvt_pk_bf16_f32 v43, v43, v44
	v_cvt_pk_bf16_f32 v44, v53, v47
	v_cvt_pk_bf16_f32 v45, v48, v45
	s_bitcmp1_b32 s98, 1
	s_cbranch_scc1 .Lmy_hs_10
	global_store_dwordx4 v[50:51], v[42:45], off
.Lmy_hs_10:
	v_max_f32_e32 v38, 0, v38
	v_max_f32_e32 v37, 0, v37
	v_mul_f32_e32 v42, v34, v34
	v_max_f32_e32 v34, 0, v39
	v_mul_f32_e32 v39, v35, v35
	v_max_f32_e32 v35, 0, v40
	v_mul_f32_e32 v40, v36, v36
	v_max_f32_e32 v36, 0, v41
	v_mul_f32_e32 v34, v34, v34
	v_mul_f32_e32 v35, v35, v35
	v_mul_f32_e32 v36, v36, v36
	v_mul_f32_e32 v38, v38, v38
	v_mul_f32_e32 v37, v37, v37
	v_cvt_pk_bf16_f32 v34, v38, v34
	v_cvt_pk_bf16_f32 v35, v35, v36
	v_cvt_pk_bf16_f32 v36, v42, v39
	s_and_b64 vcc, exec, s[40:41]
	v_cvt_pk_bf16_f32 v37, v40, v37
	s_bitcmp1_b32 s98, 1
	s_cbranch_scc1 .Lmy_hs_11
	global_store_dwordx4 v[50:51], v[34:37], off offset:256
.Lmy_hs_11:
	s_cbranch_vccnz .LBB0_737
	s_nop 1
	v_mov_b32_e32 v36, v220
	s_mov_b64 s[8:9], 0

.LBB0_739:
	v_fmamk_f32 v36, v36, 0x3a000000, v205
	v_mul_f32_e32 v37, 0x4b800000, v36
	v_cmp_gt_f32_e32 vcc, s12, v36
	v_lshlrev_b64 v[34:35], 14, v[34:35]
	v_lshl_add_u64 v[34:35], s[10:11], 0, v[34:35]
	v_cndmask_b32_e32 v36, v36, v37, vcc
	v_rsq_f32_e32 v36, v36
	v_lshl_add_u64 v[34:35], v[148:149], 1, v[34:35]
	s_mov_b64 s[8:9], -1
	v_mul_f32_e32 v37, 0x45800000, v36
	v_cndmask_b32_e32 v36, v36, v37, vcc
	v_pk_mul_f32 v[26:27], v[26:27], v[36:37] op_sel_hi:[1,0]
	v_pk_mul_f32 v[30:31], v[30:31], v[36:37] op_sel_hi:[1,0]
	v_pk_mul_f32 v[28:29], v[28:29], v[36:37] op_sel_hi:[1,0]
	v_max_f32_e32 v26, 0, v26
	v_pk_mul_f32 v[32:33], v[32:33], v[36:37] op_sel_hi:[1,0]
	v_mul_f32_e32 v37, v26, v26
	v_max_f32_e32 v26, 0, v31
	v_max_f32_e32 v27, 0, v27
	v_max_f32_e32 v28, 0, v28
	v_max_f32_e32 v30, 0, v30
	v_mul_f32_e32 v26, v26, v26
	v_mul_f32_e32 v31, v27, v27
	v_max_f32_e32 v27, 0, v32
	v_mul_f32_e32 v32, v28, v28
	v_max_f32_e32 v28, 0, v33
	v_max_f32_e32 v29, 0, v29
	v_pk_mul_f32 v[20:21], v[20:21], v[36:37] op_sel_hi:[1,0]
	v_pk_mul_f32 v[18:19], v[18:19], v[36:37] op_sel_hi:[1,0]
	v_mul_f32_e32 v30, v30, v30
	v_mul_f32_e32 v27, v27, v27
	v_mul_f32_e32 v28, v28, v28
	v_mul_f32_e32 v29, v29, v29
	v_cvt_pk_bf16_f32 v26, v30, v26
	v_pk_mul_f32 v[24:25], v[24:25], v[36:37] op_sel_hi:[1,0]
	v_pk_mul_f32 v[22:23], v[22:23], v[36:37] op_sel_hi:[1,0]
	v_max_f32_e32 v18, 0, v18
	v_max_f32_e32 v19, 0, v19
	v_max_f32_e32 v20, 0, v20
	v_cvt_pk_bf16_f32 v27, v27, v28
	v_cvt_pk_bf16_f32 v28, v37, v31
	v_cvt_pk_bf16_f32 v29, v32, v29
	s_bitcmp1_b32 s98, 1
	s_cbranch_scc1 .Lmy_hs_12
	global_store_dwordx4 v[34:35], v[26:29], off
.Lmy_hs_12:
	v_max_f32_e32 v22, 0, v22
	v_max_f32_e32 v21, 0, v21
	v_mul_f32_e32 v26, v18, v18
	v_max_f32_e32 v18, 0, v23
	v_mul_f32_e32 v23, v19, v19
	v_max_f32_e32 v19, 0, v24
	v_mul_f32_e32 v24, v20, v20
	v_max_f32_e32 v20, 0, v25
	v_mul_f32_e32 v18, v18, v18
	v_mul_f32_e32 v19, v19, v19
	v_mul_f32_e32 v20, v20, v20
	v_mul_f32_e32 v22, v22, v22
	v_mul_f32_e32 v21, v21, v21
	v_cvt_pk_bf16_f32 v18, v22, v18
	v_cvt_pk_bf16_f32 v19, v19, v20
	v_cvt_pk_bf16_f32 v20, v26, v23
	s_and_b64 vcc, exec, s[40:41]
	v_cvt_pk_bf16_f32 v21, v24, v21
	s_bitcmp1_b32 s98, 1
	s_cbranch_scc1 .Lmy_hs_13
	global_store_dwordx4 v[34:35], v[18:21], off offset:256
.Lmy_hs_13:
	s_cbranch_vccnz .LBB0_741
	s_nop 1
	v_mov_b32_e32 v20, v221
	s_mov_b64 s[8:9], 0

.LBB0_743:
	v_fmamk_f32 v20, v20, 0x3a000000, v205
	v_mul_f32_e32 v21, 0x4b800000, v20
	v_cmp_gt_f32_e32 vcc, s12, v20
	v_lshlrev_b64 v[18:19], 14, v[18:19]
	v_lshl_add_u64 v[18:19], s[10:11], 0, v[18:19]
	v_cndmask_b32_e32 v20, v20, v21, vcc
	v_rsq_f32_e32 v20, v20
	v_lshl_add_u64 v[18:19], v[148:149], 1, v[18:19]
	s_mov_b64 s[8:9], -1
	v_mul_f32_e32 v21, 0x45800000, v20
	v_cndmask_b32_e32 v20, v20, v21, vcc
	v_pk_mul_f32 v[10:11], v[10:11], v[20:21] op_sel_hi:[1,0]
	v_pk_mul_f32 v[14:15], v[14:15], v[20:21] op_sel_hi:[1,0]
	v_pk_mul_f32 v[12:13], v[12:13], v[20:21] op_sel_hi:[1,0]
	v_max_f32_e32 v10, 0, v10
	v_pk_mul_f32 v[16:17], v[16:17], v[20:21] op_sel_hi:[1,0]
	v_mul_f32_e32 v21, v10, v10
	v_max_f32_e32 v10, 0, v15
	v_max_f32_e32 v11, 0, v11
	v_max_f32_e32 v12, 0, v12
	v_max_f32_e32 v14, 0, v14
	v_mul_f32_e32 v10, v10, v10
	v_mul_f32_e32 v15, v11, v11
	v_max_f32_e32 v11, 0, v16
	v_mul_f32_e32 v16, v12, v12
	v_max_f32_e32 v12, 0, v17
	v_max_f32_e32 v13, 0, v13
	v_pk_mul_f32 v[4:5], v[4:5], v[20:21] op_sel_hi:[1,0]
	v_pk_mul_f32 v[2:3], v[2:3], v[20:21] op_sel_hi:[1,0]
	v_mul_f32_e32 v14, v14, v14
	v_mul_f32_e32 v11, v11, v11
	v_mul_f32_e32 v12, v12, v12
	v_mul_f32_e32 v13, v13, v13
	v_cvt_pk_bf16_f32 v10, v14, v10
	v_pk_mul_f32 v[8:9], v[8:9], v[20:21] op_sel_hi:[1,0]
	v_pk_mul_f32 v[6:7], v[6:7], v[20:21] op_sel_hi:[1,0]
	v_max_f32_e32 v2, 0, v2
	v_max_f32_e32 v3, 0, v3
	v_max_f32_e32 v4, 0, v4
	v_cvt_pk_bf16_f32 v11, v11, v12
	v_cvt_pk_bf16_f32 v12, v21, v15
	v_cvt_pk_bf16_f32 v13, v16, v13
	s_bitcmp1_b32 s98, 1
	s_cbranch_scc1 .Lmy_hs_14
	global_store_dwordx4 v[18:19], v[10:13], off
.Lmy_hs_14:
	v_max_f32_e32 v5, 0, v5
	v_max_f32_e32 v6, 0, v6
	v_mul_f32_e32 v10, v2, v2
	v_max_f32_e32 v2, 0, v7
	v_mul_f32_e32 v7, v3, v3
	v_max_f32_e32 v3, 0, v8
	v_mul_f32_e32 v8, v4, v4
	v_max_f32_e32 v4, 0, v9
	v_mul_f32_e32 v2, v2, v2
	v_mul_f32_e32 v3, v3, v3
	v_mul_f32_e32 v4, v4, v4
	v_mul_f32_e32 v5, v5, v5
	s_andn2_b64 vcc, exec, s[38:39]
	v_mul_f32_e32 v6, v6, v6
	v_cvt_pk_bf16_f32 v2, v6, v2
	v_cvt_pk_bf16_f32 v3, v3, v4
	v_cvt_pk_bf16_f32 v4, v10, v7
	v_cvt_pk_bf16_f32 v5, v8, v5
	s_bitcmp1_b32 s98, 1
	s_cbranch_scc1 .Lmy_hs_15
	global_store_dwordx4 v[18:19], v[2:5], off offset:256
.Lmy_hs_15:
	s_cbranch_vccnz .LBB0_704
	s_andn2_b64 vcc, exec, s[4:5]
	s_cbranch_vccnz .LBB0_703
	s_barrier
	s_branch .LBB0_703
